# attention loop: waves 4-7 issue the next tile LDS-DMA after the QK(T1) chain instead of after PV(T0)
# speedup vs baseline: 1.0077x; 1.0077x over previous
; #define LAS __attribute__((address_space(3)))
; __device__ __forceinline__ unsigned pk2(float lo, float hi) { return pg8::cvt_pk_bf16(lo, hi); }
; __device__ __forceinline__ void attn_block(LAS unsigned char* lds, const Ptrs& P, int b, int h, int qb, float negMb, float lam, int tid, int wid, int lane) {
;     ...
;             if (active) {
;                 f32x16 s;
; #pragma unroll
;                 for (int r = 0; r < 16; ++r) s[r] = negMb;
; #pragma unroll
;                 for (int ks = 0; ks < 8; ++ks) {
;                     const bf16x8 kf = *(const LAS bf16x8*)(base + koffr + T * 8192 + (((2 * ks + hhb) ^ kx) << 4));
;                     s = __builtin_amdgcn_mfma_f32_32x32x16_bf16(kf, qf[ks], s, 0, 0, 0);
;                 }
;                 float ps = 0.f;
; #pragma unroll
;                 for (int r = 0; r < 16; ++r) { s[r] = __builtin_amdgcn_exp2f(s[r]); ps += s[r]; }
;                 lsum += ps;
; #pragma unroll
;                 for (int sI = 0; sI < 2; ++sI) { v4u w;
; #pragma unroll
;                     for (int j = 0; j < 4; ++j) w[j] = pk2(s[8 * sI + 2 * j], s[8 * sI + 2 * j + 1]);
;                     const bf16x8 pf = __builtin_bit_cast(bf16x8, w);
;                     const LAS unsigned char* vb = base + voffr + (((2 * (2 * T + sI) + hhb) ^ vx) << 4);
.Lat_qk:
	ds_read_b128 v[226:229], v214
	ds_read_b128 v[230:233], v215
	ds_read_b128 v[234:237], v216
	s_waitcnt lgkmcnt(2)
	v_mfma_f32_32x32x16_bf16 v[146:161], v[226:229], v[190:193], v[2:17]
	ds_read_b128 v[226:229], v217
	s_waitcnt lgkmcnt(2)
	v_mfma_f32_32x32x16_bf16 v[146:161], v[230:233], v[186:189], v[146:161]
	ds_read_b128 v[230:233], v218
	s_waitcnt lgkmcnt(2)
	v_mfma_f32_32x32x16_bf16 v[146:161], v[234:237], v[182:185], v[146:161]
	ds_read_b128 v[234:237], v219
	s_waitcnt lgkmcnt(2)
	v_mfma_f32_32x32x16_bf16 v[146:161], v[226:229], v[178:181], v[146:161]
	ds_read_b128 v[226:229], v220
	s_waitcnt lgkmcnt(2)
	v_mfma_f32_32x32x16_bf16 v[146:161], v[230:233], v[174:177], v[146:161]
	ds_read_b128 v[230:233], v221
	s_waitcnt lgkmcnt(2)
	v_mfma_f32_32x32x16_bf16 v[146:161], v[234:237], v[166:169], v[146:161]
	ds_read_b128 v[234:237], v214 offset:8192
	s_waitcnt lgkmcnt(2)
	v_mfma_f32_32x32x16_bf16 v[146:161], v[226:229], v[170:173], v[146:161]
	ds_read_b128 v[226:229], v215 offset:8192
	s_waitcnt lgkmcnt(2)
	v_mfma_f32_32x32x16_bf16 v[146:161], v[230:233], v[162:165], v[146:161]
	ds_read_b128 v[230:233], v216 offset:8192
	s_waitcnt lgkmcnt(2)
	v_mfma_f32_32x32x16_bf16 v[238:253], v[234:237], v[190:193], v[2:17]
	ds_read_b128 v[234:237], v217 offset:8192
	s_waitcnt lgkmcnt(2)
	v_mfma_f32_32x32x16_bf16 v[238:253], v[226:229], v[186:189], v[238:253]
	ds_read_b128 v[226:229], v218 offset:8192
	s_waitcnt lgkmcnt(2)
	v_mfma_f32_32x32x16_bf16 v[238:253], v[230:233], v[182:185], v[238:253]
	ds_read_b128 v[230:233], v219 offset:8192
	s_waitcnt lgkmcnt(2)
	v_mfma_f32_32x32x16_bf16 v[238:253], v[234:237], v[178:181], v[238:253]
	ds_read_b128 v[234:237], v220 offset:8192
	v_exp_f32_e32 v146, v146
	v_exp_f32_e32 v147, v147
	v_exp_f32_e32 v148, v148
	s_waitcnt lgkmcnt(2)
	v_mfma_f32_32x32x16_bf16 v[238:253], v[226:229], v[174:177], v[238:253]
	v_exp_f32_e32 v149, v149
	v_exp_f32_e32 v150, v150
	v_exp_f32_e32 v151, v151
	ds_read_b128 v[226:229], v221 offset:8192
	s_waitcnt lgkmcnt(2)
	v_mfma_f32_32x32x16_bf16 v[238:253], v[230:233], v[166:169], v[238:253]
	v_exp_f32_e32 v152, v152
	v_exp_f32_e32 v153, v153
	v_add_f32_e32 v254, v254, v146
	v_add_f32_e32 v255, v255, v147
	ds_read_b128 v[230:233], v222 offset:32768
	s_waitcnt lgkmcnt(2)
	v_mfma_f32_32x32x16_bf16 v[238:253], v[234:237], v[170:173], v[238:253]
	v_add_f32_e32 v254, v254, v148
	v_add_f32_e32 v255, v255, v149
	v_add_f32_e32 v254, v254, v150
	v_add_f32_e32 v255, v255, v151
	v_add_f32_e32 v254, v254, v152
	ds_read_b128 v[234:237], v222 offset:36864
	s_waitcnt lgkmcnt(2)
	v_mfma_f32_32x32x16_bf16 v[238:253], v[226:229], v[162:165], v[238:253]
	v_add_f32_e32 v255, v255, v153
	v_cvt_pk_bf16_f32 v146, v146, v147
	v_cvt_pk_bf16_f32 v147, v148, v149
	v_cvt_pk_bf16_f32 v148, v150, v151
	v_cvt_pk_bf16_f32 v149, v152, v153
	ds_read_b128 v[226:229], v222 offset:40960
	s_andn2_b64 vcc, exec, s[12:13]
	s_cbranch_vccnz .Lat_pv1
	s_mov_b32 s44, m0
	s_mov_b32 m0, s84
	s_nop 0
	global_load_lds_dwordx4 v206, s[0:1]
	s_mov_b32 m0, s44
	s_add_i32 s44, s84, 0x400
	s_mov_b32 s45, m0
	s_mov_b32 m0, s44
	s_nop 0
	global_load_lds_dwordx4 v208, s[0:1]
	s_mov_b32 m0, s45
	s_add_i32 s44, s84, 0x800
	s_mov_b32 s45, m0
	s_mov_b32 m0, s44
	s_nop 0
	global_load_lds_dwordx4 v209, s[0:1]
	s_mov_b32 m0, s45
	s_add_i32 s44, s84, 0xc00
	s_mov_b32 s45, m0
	s_mov_b32 m0, s44
	s_nop 0
	global_load_lds_dwordx4 v210, s[0:1]
	s_mov_b32 m0, s45
	s_mov_b32 s44, m0
	s_mov_b32 m0, s85
	s_nop 0
	global_load_lds_dwordx4 v207, s[42:43]
	s_mov_b32 m0, s44
	s_add_i32 s44, s85, 0x400
	s_mov_b32 s45, m0
	s_mov_b32 m0, s44
	s_nop 0
	global_load_lds_dwordx4 v211, s[42:43]
	s_mov_b32 m0, s45
	s_add_i32 s44, s85, 0x800
	s_mov_b32 s45, m0
	s_mov_b32 m0, s44
	s_nop 0
	global_load_lds_dwordx4 v212, s[42:43]
	s_mov_b32 m0, s45
	s_add_i32 s44, s85, 0xc00
	s_mov_b32 s45, m0
	s_mov_b32 m0, s44
	s_nop 0
	global_load_lds_dwordx4 v213, s[42:43]
	s_mov_b32 m0, s45
; #define LAS __attribute__((address_space(3)))
; __device__ __forceinline__ unsigned pk2(float lo, float hi) { return pg8::cvt_pk_bf16(lo, hi); }
; __device__ __forceinline__ void attn_block(LAS unsigned char* lds, const Ptrs& P, int b, int h, int qb, float negMb, float lam, int tid, int wid, int lane) {
;     ...
;                 for (int sI = 0; sI < 2; ++sI) { v4u w;
; #pragma unroll
;                     for (int j = 0; j < 4; ++j) w[j] = pk2(s[8 * sI + 2 * j], s[8 * sI + 2 * j + 1]);
;                     const bf16x8 pf = __builtin_bit_cast(bf16x8, w);
;                     const LAS unsigned char* vb = base + voffr + (((2 * (2 * T + sI) + hhb) ^ vx) << 4);
; #pragma unroll
;                     for (int e = 0; e < 8; ++e) {
;                         const bf16x8 vf = *(const LAS bf16x8*)(vb + e * 4096);
;                         o[e] = __builtin_amdgcn_mfma_f32_32x32x16_bf16(vf, pf, o[e], 0, 0, 0);
;                     }
;                 }
;             }
;         }
;     }
.Lat_pv1:
	s_waitcnt lgkmcnt(2)
	v_mfma_f32_32x32x16_bf16 v[130:145], v[230:233], v[146:149], v[130:145]
	v_exp_f32_e32 v154, v154
	v_exp_f32_e32 v155, v155
	v_exp_f32_e32 v156, v156
	ds_read_b128 v[230:233], v222 offset:45056
	s_waitcnt lgkmcnt(2)
	v_mfma_f32_32x32x16_bf16 v[114:129], v[234:237], v[146:149], v[114:129]
	v_exp_f32_e32 v157, v157
	v_exp_f32_e32 v158, v158
	v_exp_f32_e32 v159, v159
	ds_read_b128 v[234:237], v222 offset:49152
	s_waitcnt lgkmcnt(2)
	v_mfma_f32_32x32x16_bf16 v[98:113], v[226:229], v[146:149], v[98:113]
	v_exp_f32_e32 v160, v160
	v_exp_f32_e32 v161, v161
	v_add_f32_e32 v254, v254, v154
	ds_read_b128 v[226:229], v222 offset:53248
	s_waitcnt lgkmcnt(2)
	v_mfma_f32_32x32x16_bf16 v[82:97], v[230:233], v[146:149], v[82:97]
	v_add_f32_e32 v255, v255, v155
	v_add_f32_e32 v254, v254, v156
	v_add_f32_e32 v255, v255, v157
	ds_read_b128 v[230:233], v222 offset:57344
	s_waitcnt lgkmcnt(2)
	v_mfma_f32_32x32x16_bf16 v[66:81], v[234:237], v[146:149], v[66:81]
	v_add_f32_e32 v254, v254, v158
	v_add_f32_e32 v255, v255, v159
	v_add_f32_e32 v254, v254, v160
	ds_read_b128 v[234:237], v222 offset:61440
	s_waitcnt lgkmcnt(2)
	v_mfma_f32_32x32x16_bf16 v[50:65], v[226:229], v[146:149], v[50:65]
	v_add_f32_e32 v255, v255, v161
	v_cvt_pk_bf16_f32 v154, v154, v155
	v_cvt_pk_bf16_f32 v155, v156, v157
	ds_read_b128 v[226:229], v223 offset:32768
	s_waitcnt lgkmcnt(2)
	v_mfma_f32_32x32x16_bf16 v[34:49], v[230:233], v[146:149], v[34:49]
	v_cvt_pk_bf16_f32 v156, v158, v159
	v_cvt_pk_bf16_f32 v157, v160, v161
	ds_read_b128 v[230:233], v223 offset:36864
	s_waitcnt lgkmcnt(2)
	v_mfma_f32_32x32x16_bf16 v[18:33], v[234:237], v[146:149], v[18:33]
	ds_read_b128 v[234:237], v223 offset:40960
	s_waitcnt lgkmcnt(2)
	v_mfma_f32_32x32x16_bf16 v[130:145], v[226:229], v[154:157], v[130:145]
	v_exp_f32_e32 v238, v238
	v_exp_f32_e32 v239, v239
	v_exp_f32_e32 v240, v240
	ds_read_b128 v[226:229], v223 offset:45056
	s_waitcnt lgkmcnt(2)
	v_mfma_f32_32x32x16_bf16 v[114:129], v[230:233], v[154:157], v[114:129]
	v_exp_f32_e32 v241, v241
	v_exp_f32_e32 v242, v242
	v_exp_f32_e32 v243, v243
	ds_read_b128 v[230:233], v223 offset:49152
	s_waitcnt lgkmcnt(2)
	v_mfma_f32_32x32x16_bf16 v[98:113], v[234:237], v[154:157], v[98:113]
	v_exp_f32_e32 v244, v244
	v_exp_f32_e32 v245, v245
	v_add_f32_e32 v254, v254, v238
	ds_read_b128 v[234:237], v223 offset:53248
	s_waitcnt lgkmcnt(2)
	v_mfma_f32_32x32x16_bf16 v[82:97], v[226:229], v[154:157], v[82:97]
	v_add_f32_e32 v255, v255, v239
	v_add_f32_e32 v254, v254, v240
	v_add_f32_e32 v255, v255, v241
	ds_read_b128 v[226:229], v223 offset:57344
	s_waitcnt lgkmcnt(2)
	v_mfma_f32_32x32x16_bf16 v[66:81], v[230:233], v[154:157], v[66:81]
	v_add_f32_e32 v254, v254, v242
	v_add_f32_e32 v255, v255, v243
	v_add_f32_e32 v254, v254, v244
	ds_read_b128 v[230:233], v223 offset:61440
	s_waitcnt lgkmcnt(2)
	v_mfma_f32_32x32x16_bf16 v[50:65], v[234:237], v[154:157], v[50:65]
	v_add_f32_e32 v255, v255, v245
	v_cvt_pk_bf16_f32 v238, v238, v239
	v_cvt_pk_bf16_f32 v239, v240, v241
	ds_read_b128 v[234:237], v224 offset:32768
	s_waitcnt lgkmcnt(2)
	v_mfma_f32_32x32x16_bf16 v[34:49], v[226:229], v[154:157], v[34:49]
	v_cvt_pk_bf16_f32 v240, v242, v243
	v_cvt_pk_bf16_f32 v241, v244, v245
	ds_read_b128 v[226:229], v224 offset:36864
	s_waitcnt lgkmcnt(2)
	v_mfma_f32_32x32x16_bf16 v[18:33], v[230:233], v[154:157], v[18:33]
	ds_read_b128 v[230:233], v224 offset:40960
	s_waitcnt lgkmcnt(2)
	v_mfma_f32_32x32x16_bf16 v[130:145], v[234:237], v[238:241], v[130:145]
	v_exp_f32_e32 v246, v246
	v_exp_f32_e32 v247, v247
	v_exp_f32_e32 v248, v248
	ds_read_b128 v[234:237], v224 offset:45056
	s_waitcnt lgkmcnt(2)
	v_mfma_f32_32x32x16_bf16 v[114:129], v[226:229], v[238:241], v[114:129]
	v_exp_f32_e32 v249, v249
	v_exp_f32_e32 v250, v250
	v_exp_f32_e32 v251, v251
	ds_read_b128 v[226:229], v224 offset:49152
	s_waitcnt lgkmcnt(2)
	v_mfma_f32_32x32x16_bf16 v[98:113], v[230:233], v[238:241], v[98:113]
	v_exp_f32_e32 v252, v252
	v_exp_f32_e32 v253, v253
	v_add_f32_e32 v254, v254, v246
	ds_read_b128 v[230:233], v224 offset:53248
	s_waitcnt lgkmcnt(2)
	v_mfma_f32_32x32x16_bf16 v[82:97], v[234:237], v[238:241], v[82:97]
	v_add_f32_e32 v255, v255, v247
	v_add_f32_e32 v254, v254, v248
	v_add_f32_e32 v255, v255, v249
	ds_read_b128 v[234:237], v224 offset:57344
	s_waitcnt lgkmcnt(2)
	v_mfma_f32_32x32x16_bf16 v[66:81], v[226:229], v[238:241], v[66:81]
	v_add_f32_e32 v254, v254, v250
	v_add_f32_e32 v255, v255, v251
	v_add_f32_e32 v254, v254, v252
	ds_read_b128 v[226:229], v224 offset:61440
	s_waitcnt lgkmcnt(2)
	v_mfma_f32_32x32x16_bf16 v[50:65], v[230:233], v[238:241], v[50:65]
	v_add_f32_e32 v255, v255, v253
	v_cvt_pk_bf16_f32 v246, v246, v247
	v_cvt_pk_bf16_f32 v247, v248, v249
	ds_read_b128 v[230:233], v225 offset:32768
	s_waitcnt lgkmcnt(2)
	v_mfma_f32_32x32x16_bf16 v[34:49], v[234:237], v[238:241], v[34:49]
	v_cvt_pk_bf16_f32 v248, v250, v251
	v_cvt_pk_bf16_f32 v249, v252, v253
	ds_read_b128 v[234:237], v225 offset:36864
	s_waitcnt lgkmcnt(2)
	v_mfma_f32_32x32x16_bf16 v[18:33], v[226:229], v[238:241], v[18:33]
	ds_read_b128 v[226:229], v225 offset:40960
	s_waitcnt lgkmcnt(2)
	v_mfma_f32_32x32x16_bf16 v[130:145], v[230:233], v[246:249], v[130:145]
	v_xor_b32_e32 v214, 0x10000, v214
	v_xor_b32_e32 v215, 0x10000, v215
	ds_read_b128 v[230:233], v225 offset:45056
	s_waitcnt lgkmcnt(2)
	v_mfma_f32_32x32x16_bf16 v[114:129], v[234:237], v[246:249], v[114:129]
	v_xor_b32_e32 v216, 0x10000, v216
	v_xor_b32_e32 v217, 0x10000, v217
	ds_read_b128 v[234:237], v225 offset:49152
	s_waitcnt lgkmcnt(2)
	v_mfma_f32_32x32x16_bf16 v[98:113], v[226:229], v[246:249], v[98:113]
	v_xor_b32_e32 v218, 0x10000, v218
	v_xor_b32_e32 v219, 0x10000, v219
	ds_read_b128 v[226:229], v225 offset:53248
	s_waitcnt lgkmcnt(2)
	v_mfma_f32_32x32x16_bf16 v[82:97], v[230:233], v[246:249], v[82:97]
	v_xor_b32_e32 v220, 0x10000, v220
	v_xor_b32_e32 v221, 0x10000, v221
	ds_read_b128 v[230:233], v225 offset:57344
	s_waitcnt lgkmcnt(2)
	v_mfma_f32_32x32x16_bf16 v[66:81], v[234:237], v[246:249], v[66:81]
	v_xor_b32_e32 v222, 0x10000, v222
	v_xor_b32_e32 v223, 0x10000, v223
	ds_read_b128 v[234:237], v225 offset:61440
	s_waitcnt lgkmcnt(2)
	v_mfma_f32_32x32x16_bf16 v[50:65], v[226:229], v[246:249], v[50:65]
	v_xor_b32_e32 v224, 0x10000, v224
	s_waitcnt lgkmcnt(1)
	v_mfma_f32_32x32x16_bf16 v[34:49], v[230:233], v[246:249], v[34:49]
	v_xor_b32_e32 v225, 0x10000, v225
	s_waitcnt lgkmcnt(0)
	v_mfma_f32_32x32x16_bf16 v[18:33], v[234:237], v[246:249], v[18:33]
	s_add_i32 s81, s81, 0x10000
	s_add_u32 s42, s42, 0x80
	s_addc_u32 s43, s43, 0
	s_add_u32 s0, s0, 0x20000
	s_addc_u32 s1, s1, 0
	s_cmp_eq_u32 s82, s81
	s_cbranch_scc0 .Lat_tile
	s_setprio 0
	s_not_b64 s[2:3], s[12:13]
	s_nop 0
	v_add_f32_e32 v194, v194, v254
	v_add_f32_e32 v194, v194, v255
